# v25: v23 + next-item L2 prefetch in both weight-conversion loops (phase A and phase 0)
# baseline (speedup 1.0000x reference)
.LBB0_43:
	s_lshl_b32 s18, s36, 6
	v_lshlrev_b32_e32 v3, 4, v2
	s_and_b32 s36, s18, 0x3c0
	s_lshl_b64 s[18:19], s[26:27], 2
	v_and_b32_e32 v14, 0xf0, v3
	v_ashrrev_i32_e32 v3, 4, v2
	s_waitcnt lgkmcnt(0)
	s_add_u32 s14, s14, s18
	v_add_u32_e32 v18, s36, v3
	s_addc_u32 s15, s15, s19
	v_ashrrev_i32_e32 v19, 31, v18
	v_lshl_add_u64 v[4:5], s[14:15], 0, v[14:15]
	v_mul_lo_u32 v23, s16, v19
	v_mul_lo_u32 v24, s17, v18
	v_mad_u64_u32 v[18:19], s[14:15], s16, v18, 0
	v_add3_u32 v19, v19, v23, v24
	v_lshl_add_u64 v[18:19], v[18:19], 2, v[4:5]
	s_cmpk_lt_i32 s73, 0xae2
	s_cselect_b32 s100, 0x1000, 0
	s_mov_b32 s101, 0
	v_lshl_add_u64 v[204:205], v[18:19], 0, s[100:101]
	global_load_dwordx4 v[24:27], v[18:19], off
	v_add_u32_e32 v18, 0x200, v2
	v_ashrrev_i32_e32 v23, 4, v18
	v_add_u32_e32 v14, s59, v14
	v_add_u32_e32 v28, s36, v23
	v_mad_u64_u32 v[18:19], s[14:15], v3, s60, v[14:15]
	v_ashrrev_i32_e32 v3, 31, v28
	v_mul_lo_u32 v19, s17, v28
	v_mad_u64_u32 v[28:29], s[14:15], s16, v28, 0
	v_mul_lo_u32 v3, s16, v3
	v_add3_u32 v29, v29, v3, v19
	v_lshl_add_u64 v[4:5], v[28:29], 2, v[4:5]
	global_load_dwordx4 v[200:203], v[4:5], off
	v_lshl_add_u64 v[206:207], v[4:5], 0, s[100:101]
	global_load_dword v224, v[204:205], off
	global_load_dword v224, v[206:207], off
	s_lshl_b32 s26, s36, 1
	s_mov_b64 s[36:37], -1
	s_waitcnt vmcnt(3) lgkmcnt(0)
	ds_write2_b32 v18, v24, v25 offset1:1
	ds_write2_b32 v18, v26, v27 offset0:2 offset1:3
	v_ashrrev_i32_e32 v4, 3, v2
	v_lshlrev_b32_e32 v2, 3, v2
	v_and_b32_e32 v18, 56, v2
	v_lshlrev_b32_e32 v19, 2, v4
	v_ashrrev_i32_e32 v5, 31, v4
	v_mul_u32_u24_e32 v28, 0x104, v18
	v_lshlrev_b64 v[2:3], 11, v[4:5]
	v_mad_u64_u32 v[4:5], s[16:17], v23, s60, v[14:15]
	v_add3_u32 v19, s59, v28, v19
	v_add_u32_e32 v23, 0x400, v19
	v_lshlrev_b32_e32 v14, 1, v18
	v_lshl_add_u64 v[2:3], s[12:13], 0, v[2:3]
	v_lshl_add_u64 v[2:3], v[2:3], 0, s[26:27]
	v_lshl_add_u64 v[28:29], v[2:3], 0, v[14:15]
	s_waitcnt vmcnt(2) lgkmcnt(0)
	ds_write2_b32 v4, v200, v201 offset1:1
	ds_write2_b32 v4, v202, v203 offset0:2 offset1:3
	s_waitcnt lgkmcnt(0)
	s_barrier
	ds_read2_b32 v[4:5], v19 offset1:65
	ds_read2_b32 v[18:19], v19 offset0:130 offset1:195
	ds_read2_b32 v[24:25], v23 offset0:4 offset1:69
	ds_read2_b32 v[26:27], v23 offset0:134 offset1:199
	s_waitcnt lgkmcnt(3)
	s_nop 1
	v_cvt_pk_bf16_f32 v2, v4, v5
	s_waitcnt lgkmcnt(2)
	s_nop 1
	v_cvt_pk_bf16_f32 v3, v18, v19
	s_waitcnt lgkmcnt(1)
	s_nop 1
	v_cvt_pk_bf16_f32 v4, v24, v25
	s_waitcnt lgkmcnt(0)
	s_nop 1
	v_cvt_pk_bf16_f32 v5, v26, v27
	global_store_dwordx4 v[28:29], v[2:5], off
	s_barrier
	s_branch .LBB0_57
